# stagger also in N=1024 GEMM phases (all GEMM phases), step 0.35us
# baseline (speedup 1.0000x reference)
.LBB0_96:
	s_lshl_b32 s2, 1, s55
	s_and_b32 s2, s2, 0x15554
	s_cbranch_scc0 .Lstg_skip
	s_lshr_b32 s2, s54, 3
	s_and_b32 s2, s2, 7
